# software-pipelined prompt diff-attention loop plus hazard padding in the rare rescale path
# speedup vs baseline: 1.0080x; 1.0046x over previous
; template <bool WIN> ...
;     ...
;             if (__any(mx > THR)) {
;                 mx = fmaxf(mx, __shfl_xor(mx, 32));
;                 const float dl = fmaxf(mx, 0.f);
;                 m_ref += dl;
;                 const float f = __builtin_amdgcn_exp2f(-dl);
;                 l_run *= f;
; #pragma unroll
;                 for (int db = 0; db < NDB; ++db)
; #pragma unroll
;                     for (int r = 0; r < 16; ++r) o[db][r] *= f;
; #pragma unroll
;                 for (int r = 0; r < 16; ++r) { s0[r] -= dl; s1[r] -= dl; cvec[r] = cbase - m_ref; }
;             }
;     ...
;             for (int db = 0; db < NDB; ++db) o[db] = __builtin_amdgcn_mfma_f32_32x32x16_bf16(va[db], p0.b, o[db], 0, 0, 0);
;             AT_EXP(s0, 8, p1);
;             __builtin_amdgcn_sched_barrier(0);
; #pragma unroll
;             for (int db = 0; db < NDB; ++db) o[db] = __builtin_amdgcn_mfma_f32_32x32x16_bf16(va[NDB + db], p1.b, o[db], 0, 0, 0);
;             AT_EXP(s1, 0, p2);
;             __builtin_amdgcn_sched_barrier(0);
; #pragma unroll
;             for (int db = 0; db < NDB; ++db) o[db] = __builtin_amdgcn_mfma_f32_32x32x16_bf16(vc[db], p2.b, o[db], 0, 0, 0);
;             AT_EXP(s1, 8, p3);
;             __builtin_amdgcn_sched_barrier(0);
; #pragma unroll
;             for (int db = 0; db < NDB; ++db) o[db] = __builtin_amdgcn_mfma_f32_32x32x16_bf16(vc[NDB + db], p3.b, o[db], 0, 0, 0);
.LSPp_max:
	s_nop 0
	v_max_f32_e32 v203, v99, v99
	v_max_f32_e32 v204, v98, v98
	v_max_f32_e32 v203, v204, v203
	s_nop 5
	v_max3_f32 v204, v100, v101, v83
	v_max3_f32 v203, v203, v82, v84
	v_max3_f32 v203, v203, v85, v102
	v_max3_f32 v204, v204, v104, v105
	v_max3_f32 v203, v203, v103, v86
	v_max3_f32 v204, v204, v88, v89
	v_max3_f32 v203, v203, v87, v106
	v_max3_f32 v204, v204, v108, v109
	v_max3_f32 v203, v203, v107, v90
	v_max3_f32 v204, v204, v92, v93
	v_max3_f32 v203, v203, v91, v110
	v_max3_f32 v204, v204, v112, v113
	v_max3_f32 v203, v203, v111, v94
	v_max3_f32 v204, v204, v96, v97
	v_max3_f32 v203, v203, v95, v204
	v_cmp_lt_f32_e32 vcc, s30, v203
	s_cbranch_vccz .LSPp_pv
	s_cmp_eq_u32 s86, 0
	s_cbranch_scc1 .LSPp_rnopv
	s_waitcnt lgkmcnt(0)
	v_add3_u32 v236, s99, v179, v187
	ds_read_b128 v[146:149], v236 offset:16384
	ds_read_b128 v[150:153], v236 offset:20480
	ds_read_b128 v[154:157], v236 offset:24576
	ds_read_b128 v[158:161], v236 offset:28672
	v_add3_u32 v237, s99, v181, v187
	ds_read_b128 v[130:133], v237 offset:16384
	ds_read_b128 v[134:137], v237 offset:20480
	ds_read_b128 v[138:141], v237 offset:24576
	ds_read_b128 v[142:145], v237 offset:28672
	s_waitcnt lgkmcnt(4)
	v_mfma_f32_32x32x16_bf16 v[50:65], v[146:149], v[238:241], v[50:65]
	v_mfma_f32_32x32x16_bf16 v[34:49], v[150:153], v[238:241], v[34:49]
	v_mfma_f32_32x32x16_bf16 v[18:33], v[154:157], v[238:241], v[18:33]
	v_mfma_f32_32x32x16_bf16 v[2:17], v[158:161], v[238:241], v[2:17]
	v_add3_u32 v236, s99, v183, v187
	ds_read_b128 v[146:149], v236 offset:16384
	ds_read_b128 v[150:153], v236 offset:20480
	ds_read_b128 v[154:157], v236 offset:24576
	ds_read_b128 v[158:161], v236 offset:28672
	s_waitcnt lgkmcnt(4)
	v_mfma_f32_32x32x16_bf16 v[50:65], v[130:133], v[242:245], v[50:65]
	v_mfma_f32_32x32x16_bf16 v[34:49], v[134:137], v[242:245], v[34:49]
	v_mfma_f32_32x32x16_bf16 v[18:33], v[138:141], v[242:245], v[18:33]
	v_mfma_f32_32x32x16_bf16 v[2:17], v[142:145], v[242:245], v[2:17]
	v_add3_u32 v237, s99, v190, v187
	ds_read_b128 v[130:133], v237 offset:16384
	ds_read_b128 v[134:137], v237 offset:20480
	ds_read_b128 v[138:141], v237 offset:24576
	ds_read_b128 v[142:145], v237 offset:28672
	s_waitcnt lgkmcnt(4)
	v_mfma_f32_32x32x16_bf16 v[50:65], v[146:149], v[246:249], v[50:65]
	v_mfma_f32_32x32x16_bf16 v[34:49], v[150:153], v[246:249], v[34:49]
	v_mfma_f32_32x32x16_bf16 v[18:33], v[154:157], v[246:249], v[18:33]
	v_mfma_f32_32x32x16_bf16 v[2:17], v[158:161], v[246:249], v[2:17]
	s_waitcnt lgkmcnt(0)
	v_mfma_f32_32x32x16_bf16 v[50:65], v[130:133], v[250:253], v[50:65]
	v_mfma_f32_32x32x16_bf16 v[34:49], v[134:137], v[250:253], v[34:49]
	v_mfma_f32_32x32x16_bf16 v[18:33], v[138:141], v[250:253], v[18:33]
	v_mfma_f32_32x32x16_bf16 v[2:17], v[142:145], v[250:253], v[2:17]
	s_nop 7
	s_nop 7
